# v8: v7 + lambda dot-product loads all in flight (ordered fma chain kept)
# speedup vs baseline: 1.0481x; 1.0153x over previous
; DI void phase_attn(int l, half_t* big, bool need_ctx, char* smem, int wv_) {
;     ...
;   const float lam_init = 0.8f - 0.6f * expf(-0.3f * (float)l);
;   float lam;
;   {
;     float d1 = 0.f, d2 = 0.f;
; #pragma unroll 1
;     for (int i = 0; i < 32; ++i) {
;       d1 += p->lq1[l * 32 + i] * p->lk1[l * 32 + i];
;       d2 += p->lq2[l * 32 + i] * p->lk2[l * 32 + i];
;     }
;     lam = expf(d1) - expf(d2) + lam_init;
;     lam = __builtin_bit_cast(float, __builtin_amdgcn_readfirstlane(__builtin_bit_cast(int, lam)));
.LBB0_1899:
	s_or_b64 exec, exec, s[60:61]
	s_mov_b64 s[10:11], s[0:1]
	s_waitcnt lgkmcnt(0)
	s_barrier
	s_load_dwordx8 s[12:19], s[10:11], 0xa0
	s_lshl_b64 s[2:3], s[52:53], 7
	s_waitcnt vmcnt(0)
	v_mov_b32_e32 v3, 0
	v_mov_b32_e32 v2, 0
	s_waitcnt lgkmcnt(0)
	s_add_u32 s4, s18, s2
	s_addc_u32 s5, s19, s3
	s_add_u32 s6, s16, s2
	s_addc_u32 s7, s17, s3
	s_add_u32 s8, s14, s2
	s_addc_u32 s9, s15, s3
	s_add_u32 s12, s12, s2
	s_addc_u32 s13, s13, s3
	global_load_dword v32, v0, s[12:13] offset:0
	global_load_dword v34, v0, s[8:9] offset:0
	global_load_dword v33, v0, s[6:7] offset:0
	global_load_dword v35, v0, s[4:5] offset:0
	global_load_dword v36, v0, s[12:13] offset:4
	global_load_dword v38, v0, s[8:9] offset:4
	global_load_dword v37, v0, s[6:7] offset:4
	global_load_dword v39, v0, s[4:5] offset:4
	global_load_dword v40, v0, s[12:13] offset:8
	global_load_dword v42, v0, s[8:9] offset:8
	global_load_dword v41, v0, s[6:7] offset:8
	global_load_dword v43, v0, s[4:5] offset:8
	global_load_dword v44, v0, s[12:13] offset:12
	global_load_dword v46, v0, s[8:9] offset:12
	global_load_dword v45, v0, s[6:7] offset:12
	global_load_dword v47, v0, s[4:5] offset:12
	global_load_dword v48, v0, s[12:13] offset:16
	global_load_dword v50, v0, s[8:9] offset:16
	global_load_dword v49, v0, s[6:7] offset:16
	global_load_dword v51, v0, s[4:5] offset:16
	global_load_dword v52, v0, s[12:13] offset:20
	global_load_dword v54, v0, s[8:9] offset:20
	global_load_dword v53, v0, s[6:7] offset:20
	global_load_dword v55, v0, s[4:5] offset:20
	global_load_dword v56, v0, s[12:13] offset:24
	global_load_dword v58, v0, s[8:9] offset:24
	global_load_dword v57, v0, s[6:7] offset:24
	global_load_dword v59, v0, s[4:5] offset:24
	global_load_dword v60, v0, s[12:13] offset:28
	global_load_dword v62, v0, s[8:9] offset:28
	global_load_dword v61, v0, s[6:7] offset:28
	global_load_dword v63, v0, s[4:5] offset:28
	global_load_dword v64, v0, s[12:13] offset:32
	global_load_dword v66, v0, s[8:9] offset:32
	global_load_dword v65, v0, s[6:7] offset:32
	global_load_dword v67, v0, s[4:5] offset:32
	global_load_dword v68, v0, s[12:13] offset:36
	global_load_dword v70, v0, s[8:9] offset:36
	global_load_dword v69, v0, s[6:7] offset:36
	global_load_dword v71, v0, s[4:5] offset:36
	global_load_dword v72, v0, s[12:13] offset:40
	global_load_dword v74, v0, s[8:9] offset:40
	global_load_dword v73, v0, s[6:7] offset:40
	global_load_dword v75, v0, s[4:5] offset:40
	global_load_dword v76, v0, s[12:13] offset:44
	global_load_dword v78, v0, s[8:9] offset:44
	global_load_dword v77, v0, s[6:7] offset:44
	global_load_dword v79, v0, s[4:5] offset:44
	global_load_dword v144, v0, s[12:13] offset:48
	global_load_dword v146, v0, s[8:9] offset:48
	global_load_dword v145, v0, s[6:7] offset:48
	global_load_dword v147, v0, s[4:5] offset:48
	global_load_dword v148, v0, s[12:13] offset:52
	global_load_dword v150, v0, s[8:9] offset:52
	global_load_dword v149, v0, s[6:7] offset:52
	global_load_dword v151, v0, s[4:5] offset:52
	global_load_dword v152, v0, s[12:13] offset:56
	global_load_dword v154, v0, s[8:9] offset:56
	global_load_dword v153, v0, s[6:7] offset:56
	global_load_dword v155, v0, s[4:5] offset:56
	global_load_dword v156, v0, s[12:13] offset:60
	global_load_dword v158, v0, s[8:9] offset:60
	global_load_dword v157, v0, s[6:7] offset:60
	global_load_dword v159, v0, s[4:5] offset:60
	global_load_dword v160, v0, s[12:13] offset:64
	global_load_dword v162, v0, s[8:9] offset:64
	global_load_dword v161, v0, s[6:7] offset:64
	global_load_dword v163, v0, s[4:5] offset:64
	global_load_dword v164, v0, s[12:13] offset:68
	global_load_dword v166, v0, s[8:9] offset:68
	global_load_dword v165, v0, s[6:7] offset:68
	global_load_dword v167, v0, s[4:5] offset:68
	global_load_dword v168, v0, s[12:13] offset:72
	global_load_dword v170, v0, s[8:9] offset:72
	global_load_dword v169, v0, s[6:7] offset:72
	global_load_dword v171, v0, s[4:5] offset:72
	global_load_dword v172, v0, s[12:13] offset:76
	global_load_dword v174, v0, s[8:9] offset:76
	global_load_dword v173, v0, s[6:7] offset:76
	global_load_dword v175, v0, s[4:5] offset:76
	global_load_dword v176, v0, s[12:13] offset:80
	global_load_dword v178, v0, s[8:9] offset:80
	global_load_dword v177, v0, s[6:7] offset:80
	global_load_dword v179, v0, s[4:5] offset:80
	global_load_dword v180, v0, s[12:13] offset:84
	global_load_dword v182, v0, s[8:9] offset:84
	global_load_dword v181, v0, s[6:7] offset:84
	global_load_dword v183, v0, s[4:5] offset:84
	global_load_dword v184, v0, s[12:13] offset:88
	global_load_dword v186, v0, s[8:9] offset:88
	global_load_dword v185, v0, s[6:7] offset:88
	global_load_dword v187, v0, s[4:5] offset:88
	global_load_dword v188, v0, s[12:13] offset:92
	global_load_dword v190, v0, s[8:9] offset:92
	global_load_dword v189, v0, s[6:7] offset:92
	global_load_dword v191, v0, s[4:5] offset:92
	global_load_dword v192, v0, s[12:13] offset:96
	global_load_dword v194, v0, s[8:9] offset:96
	global_load_dword v193, v0, s[6:7] offset:96
	global_load_dword v195, v0, s[4:5] offset:96
	global_load_dword v196, v0, s[12:13] offset:100
	global_load_dword v198, v0, s[8:9] offset:100
	global_load_dword v197, v0, s[6:7] offset:100
	global_load_dword v199, v0, s[4:5] offset:100
	global_load_dword v200, v0, s[12:13] offset:104
	global_load_dword v202, v0, s[8:9] offset:104
	global_load_dword v201, v0, s[6:7] offset:104
	global_load_dword v203, v0, s[4:5] offset:104
	global_load_dword v204, v0, s[12:13] offset:108
	global_load_dword v206, v0, s[8:9] offset:108
	global_load_dword v205, v0, s[6:7] offset:108
	global_load_dword v207, v0, s[4:5] offset:108
	global_load_dword v208, v0, s[12:13] offset:112
	global_load_dword v210, v0, s[8:9] offset:112
	global_load_dword v209, v0, s[6:7] offset:112
	global_load_dword v211, v0, s[4:5] offset:112
	global_load_dword v212, v0, s[12:13] offset:116
	global_load_dword v214, v0, s[8:9] offset:116
	global_load_dword v213, v0, s[6:7] offset:116
	global_load_dword v215, v0, s[4:5] offset:116
	global_load_dword v216, v0, s[12:13] offset:120
	global_load_dword v218, v0, s[8:9] offset:120
	global_load_dword v217, v0, s[6:7] offset:120
	global_load_dword v219, v0, s[4:5] offset:120
	global_load_dword v220, v0, s[12:13] offset:124
	global_load_dword v222, v0, s[8:9] offset:124
	global_load_dword v221, v0, s[6:7] offset:124
	global_load_dword v223, v0, s[4:5] offset:124
	s_waitcnt vmcnt(0)
; DI void phase_attn(int l, half_t* big, bool need_ctx, char* smem, int wv_) {
;     ...
;   const float lam_init = 0.8f - 0.6f * expf(-0.3f * (float)l);
;   float lam;
;   {
;     float d1 = 0.f, d2 = 0.f;
; #pragma unroll 1
;     for (int i = 0; i < 32; ++i) {
;       d1 += p->lq1[l * 32 + i] * p->lk1[l * 32 + i];
;       d2 += p->lq2[l * 32 + i] * p->lk2[l * 32 + i];
;     }
;     lam = expf(d1) - expf(d2) + lam_init;
;     lam = __builtin_bit_cast(float, __builtin_amdgcn_readfirstlane(__builtin_bit_cast(int, lam)));
;   }
;   const float one_m_li = __builtin_bit_cast(float, __builtin_amdgcn_readfirstlane(__builtin_bit_cast(int, 1.f - lam_init)));
	v_pk_fma_f32 v[2:3], v[32:33], v[34:35], v[2:3]
	v_pk_fma_f32 v[2:3], v[36:37], v[38:39], v[2:3]
	v_pk_fma_f32 v[2:3], v[40:41], v[42:43], v[2:3]
	v_pk_fma_f32 v[2:3], v[44:45], v[46:47], v[2:3]
	v_pk_fma_f32 v[2:3], v[48:49], v[50:51], v[2:3]
	v_pk_fma_f32 v[2:3], v[52:53], v[54:55], v[2:3]
	v_pk_fma_f32 v[2:3], v[56:57], v[58:59], v[2:3]
	v_pk_fma_f32 v[2:3], v[60:61], v[62:63], v[2:3]
	v_pk_fma_f32 v[2:3], v[64:65], v[66:67], v[2:3]
	v_pk_fma_f32 v[2:3], v[68:69], v[70:71], v[2:3]
	v_pk_fma_f32 v[2:3], v[72:73], v[74:75], v[2:3]
	v_pk_fma_f32 v[2:3], v[76:77], v[78:79], v[2:3]
	v_pk_fma_f32 v[2:3], v[144:145], v[146:147], v[2:3]
	v_pk_fma_f32 v[2:3], v[148:149], v[150:151], v[2:3]
	v_pk_fma_f32 v[2:3], v[152:153], v[154:155], v[2:3]
	v_pk_fma_f32 v[2:3], v[156:157], v[158:159], v[2:3]
	v_pk_fma_f32 v[2:3], v[160:161], v[162:163], v[2:3]
	v_pk_fma_f32 v[2:3], v[164:165], v[166:167], v[2:3]
	v_pk_fma_f32 v[2:3], v[168:169], v[170:171], v[2:3]
	v_pk_fma_f32 v[2:3], v[172:173], v[174:175], v[2:3]
	v_pk_fma_f32 v[2:3], v[176:177], v[178:179], v[2:3]
	v_pk_fma_f32 v[2:3], v[180:181], v[182:183], v[2:3]
	v_pk_fma_f32 v[2:3], v[184:185], v[186:187], v[2:3]
	v_pk_fma_f32 v[2:3], v[188:189], v[190:191], v[2:3]
	v_pk_fma_f32 v[2:3], v[192:193], v[194:195], v[2:3]
	v_pk_fma_f32 v[2:3], v[196:197], v[198:199], v[2:3]
	v_pk_fma_f32 v[2:3], v[200:201], v[202:203], v[2:3]
	v_pk_fma_f32 v[2:3], v[204:205], v[206:207], v[2:3]
	v_pk_fma_f32 v[2:3], v[208:209], v[210:211], v[2:3]
	v_pk_fma_f32 v[2:3], v[212:213], v[214:215], v[2:3]
	v_pk_fma_f32 v[2:3], v[216:217], v[218:219], v[2:3]
	v_pk_fma_f32 v[2:3], v[220:221], v[222:223], v[2:3]
	v_cvt_f32_u32_e32 v1, s52
	s_mov_b32 s2, 0x3fb8aa3b
	s_mov_b32 s3, 0xc2ce8ed0
	s_mov_b32 s4, 0x42b17218
	v_mul_f32_e32 v1, 0xbe99999a, v1
	v_mul_f32_e32 v4, 0x3fb8aa3b, v1
	v_fma_f32 v5, v1, s2, -v4
	v_rndne_f32_e32 v6, v4
	v_fmac_f32_e32 v5, 0x32a5705f, v1
	v_sub_f32_e32 v4, v4, v6
	v_add_f32_e32 v4, v4, v5
	v_exp_f32_e32 v4, v4
	v_cvt_i32_f32_e32 v5, v6
	v_cmp_ngt_f32_e32 vcc, s3, v1
	v_mov_b32_e32 v7, 0x7f800000
	s_mov_b32 s34, 0
	v_ldexp_f32 v4, v4, v5
	v_cndmask_b32_e32 v4, 0, v4, vcc
	v_cmp_nlt_f32_e32 vcc, s4, v1
	s_nop 1
	v_cndmask_b32_e32 v1, v7, v4, vcc
	v_mov_b32_e32 v4, 0x3f4ccccd
	v_fmamk_f32 v1, v1, 0xbf19999a, v4
	v_mul_f32_e32 v4, 0x3fb8aa3b, v2
	v_rndne_f32_e32 v5, v4
	v_sub_f32_e32 v6, v4, v5
	v_fma_f32 v4, v2, s2, -v4
	v_fmac_f32_e32 v4, 0x32a5705f, v2
	v_add_f32_e32 v4, v6, v4
	v_exp_f32_e32 v4, v4
	v_cvt_i32_f32_e32 v5, v5
	v_cmp_ngt_f32_e32 vcc, s3, v2
	v_ldexp_f32 v4, v4, v5
	s_nop 0
	v_cndmask_b32_e32 v4, 0, v4, vcc
	v_cmp_nlt_f32_e32 vcc, s4, v2
	s_nop 1
	v_cndmask_b32_e32 v2, v7, v4, vcc
	v_mul_f32_e32 v4, 0x3fb8aa3b, v3
	v_rndne_f32_e32 v5, v4
	v_sub_f32_e32 v6, v4, v5
	v_fma_f32 v4, v3, s2, -v4
	v_fmac_f32_e32 v4, 0x32a5705f, v3
	v_add_f32_e32 v4, v6, v4
	v_exp_f32_e32 v4, v4
	v_cvt_i32_f32_e32 v5, v5
	v_cmp_ngt_f32_e32 vcc, s3, v3
	v_readfirstlane_b32 s2, v1
	v_ldexp_f32 v4, v4, v5
	v_cndmask_b32_e32 v4, 0, v4, vcc
	v_cmp_nlt_f32_e32 vcc, s4, v3
	v_sub_f32_e64 v238, 1.0, s2
	v_readlane_b32 s2, v254, 57
	v_cndmask_b32_e32 v3, v7, v4, vcc
	v_sub_f32_e32 v2, v2, v3
	v_readlane_b32 s3, v254, 58
	v_add_f32_e32 v2, v1, v2
	s_and_b64 s[2:3], s[2:3], exec
	v_readfirstlane_b32 s12, v2
	s_movk_i32 s2, 0x140
	s_cselect_b32 s30, s2, 0x100
	s_lshl_b32 s31, s52, 2
	s_mov_b32 s13, s12
	s_branch .LBB0_1903
